# static s_setprio 1 for workgroups 256..511 during the NSA phase (one priority raise for the second co-resident workgroup)
# speedup vs baseline: 1.0109x; 1.0109x over previous
.LBB0_1464:
	s_or_b64 exec, exec, s[0:1]
	s_andn2_b64 vcc, exec, s[18:19]
	s_waitcnt lgkmcnt(0)
	s_barrier
	s_cbranch_vccnz .LBB0_1682
	s_cmpk_gt_u32 s2, 0xff
	s_cbranch_scc0 .Lnsa_prio0
	s_setprio 1
.Lnsa_prio0:
	s_add_u32 s100, s72, 0x2f80000
	s_addc_u32 s101, s73, 0
	s_mov_b32 s98, 0x2000
	s_mov_b32 s99, 0
	v_lshrrev_b32_e32 v244, 4, v220
	v_and_b32_e32 v245, 3, v244
	v_lshrrev_b32_e32 v246, 7, v220
	v_lshl_or_b32 v245, v246, 2, v245
	v_and_b32_e32 v246, 15, v220
	v_xor_b32_e32 v245, v245, v246
	v_lshlrev_b32_e32 v245, 4, v245
	v_lshl_or_b32 v249, v244, 8, v245
	v_xor_b32_e32 v250, 0x80, v249
	v_and_b32_e32 v245, 7, v244
	v_and_b32_e32 v246, 7, v220
	v_xor_b32_e32 v245, v245, v246
	v_lshlrev_b32_e32 v245, 4, v245
	v_lshrrev_b32_e32 v246, 3, v220
	v_lshl_or_b32 v251, v246, 7, v245
	v_lshlrev_b32_e32 v252, 4, v220
	v_add_u32_e32 v252, 0x1000, v252
	v_mov_b32_e32 v253, 0
	s_mov_b32 s57, 0
	s_cmpk_lg_i32 s74, 0x200
	s_mov_b32 s3, s57
	s_cselect_b64 s[52:53], -1, 0
	s_lshr_b32 s0, s2, 8
	s_lshl_b64 s[58:59], s[2:3], 8
	s_add_u32 s60, s72, 0x13200000
	s_addc_u32 s61, s73, 0
	s_add_u32 s62, s72, 0x3000000
	s_addc_u32 s63, s73, 0
	s_add_u32 s3, s72, 0x3600000
	s_addc_u32 s87, s73, 0
	s_add_u32 s88, s72, 0x3800000
	s_addc_u32 s89, s73, 0
	s_add_u32 s64, s72, 0x7200000
	s_addc_u32 s65, s73, 0
	s_add_u32 s90, s72, 0xb200000
	s_addc_u32 s91, s73, 0
	v_writelane_b32 v254, s54, 32
	s_add_u32 s92, s72, 0xd200000
	s_addc_u32 s93, s73, 0
	v_writelane_b32 v254, s55, 33
	v_writelane_b32 v254, s0, 24
	s_add_u32 s0, s72, 0x11200000
	v_writelane_b32 v254, s0, 22
	s_addc_u32 s0, s73, 0
	s_add_u32 s96, s72, 0xf200000
	s_addc_u32 s97, s73, 0
	s_movk_i32 s4, 0x1ff
	s_waitcnt vmcnt(15)
	v_mov_b32_e32 v168, 0x10200
	v_mov_b32_e32 v17, 0
	s_mov_b32 s5, 0x8000
	s_movk_i32 s8, 0x400
	s_movk_i32 s9, 0x7fff
	v_mov_b32_e32 v169, 0xf149f2ca
	v_mbcnt_hi_u32_b32 v170, -1, v221
	v_mov_b32_e32 v171, 0xc0
	v_mov_b32_e32 v172, 0x7149f200
	v_mov_b32_e32 v173, 0x7149f2ca
	v_mov_b32_e32 v174, 1
	s_mov_b32 s6, s2
	v_writelane_b32 v254, s0, 26
	s_branch .LBB0_1468

.LBB0_1682:
	s_setprio 0
	s_waitcnt vmcnt(0)
	s_barrier
	s_mov_b64 s[0:1], exec
	v_readlane_b32 s4, v254, 0
	v_readlane_b32 s5, v254, 1
	s_and_b64 s[4:5], s[0:1], s[4:5]
	s_mov_b64 exec, s[4:5]
	s_cbranch_execz .LBB0_1734
	v_mov_b32_e32 v0, 0x10600
	s_waitcnt vmcnt(0) expcnt(0) lgkmcnt(0)
	ds_read_b32 v2, v0
	v_mov_b32_e32 v0, 0x10604
	ds_read_b32 v0, v0
	s_waitcnt lgkmcnt(1)
	v_cmp_ne_u32_e32 vcc, 0, v2
	s_cbranch_vccnz .LBB0_1698
	s_add_u32 s10, s72, 0x2f80200
	s_addc_u32 s11, s73, 0
	s_add_u32 s12, s72, 0x2f80400
	s_addc_u32 s13, s73, 0
	s_add_u32 s14, s72, 0x2f80500
	s_addc_u32 s15, s73, 0
	s_add_u32 s16, s72, 0x2f80600
	s_addc_u32 s17, s73, 0
	s_add_u32 s18, s72, 0x2f80700
	s_addc_u32 s19, s73, 0
	s_add_u32 s20, s72, 0x2f80800
	s_addc_u32 s21, s73, 0
	s_add_u32 s22, s72, 0x2f80900
	s_addc_u32 s23, s73, 0
	s_add_u32 s24, s72, 0x2f80a00
	s_addc_u32 s25, s73, 0
	s_add_u32 s26, s72, 0x2f80b00
	s_addc_u32 s27, s73, 0
	s_add_u32 s28, s72, 0x2f80c00
	s_addc_u32 s29, s73, 0
	s_add_u32 s30, s72, 0x2f80d00
	s_addc_u32 s31, s73, 0
	s_add_u32 s34, s72, 0x2f80e00
	s_addc_u32 s35, s73, 0
	s_add_u32 s36, s72, 0x2f80f00
	s_addc_u32 s37, s73, 0
	s_add_u32 s38, s72, 0x2f81000
	s_addc_u32 s39, s73, 0
	s_add_u32 s40, s72, 0x2f81100
	s_addc_u32 s41, s73, 0
	s_add_u32 s42, s72, 0x2f81200
	v_readlane_b32 s3, v254, 2
	s_addc_u32 s43, s73, 0
	s_mul_i32 s3, s75, s3
	s_add_u32 s44, s72, 0x2f81300
	s_mul_i32 s3, s3, s74
	s_addc_u32 s45, s73, 0
	s_mov_b32 s4, 1
	v_mov_b32_e32 v16, 0
	s_branch .LBB0_1686
